# SWA attention LDS rows restrided too (K and V^T 144->160 B) for bank-conflict-free 16x16x32 fragment reads
# speedup vs baseline: 1.0239x; 1.0013x over previous
.LBB0_274:
	s_or_b64 exec, exec, s[4:5]
	s_cmpk_lt_i32 s2, 0x400
	s_cselect_b64 s[0:1], -1, 0
	v_writelane_b32 v246, s0, 40
	s_cmpk_lt_i32 s2, 0x100
	s_mul_i32 s31, s31, s30
	v_writelane_b32 v246, s1, 41
	s_cselect_b64 s[0:1], -1, 0
	v_writelane_b32 v246, s0, 42
	s_mul_i32 s31, s31, s3
	s_movk_i32 s78, 0x400
	v_writelane_b32 v246, s1, 43
	s_movk_i32 s28, 0x600
	v_readlane_b32 s4, v246, 0
	v_readlane_b32 s16, v246, 12
	v_readlane_b32 s17, v246, 13
	s_cmp_lg_u64 s[16:17], 0
	s_cselect_b64 s[34:35], -1, 0
	s_cmpk_lt_i32 s2, 0xc0
	s_cselect_b64 s[0:1], -1, 0
	s_lshl_b32 s71, s30, 3
	v_readlane_b32 s5, v246, 1
	v_readlane_b32 s6, v246, 2
	v_readlane_b32 s7, v246, 3
	v_readlane_b32 s8, v246, 4
	v_readlane_b32 s9, v246, 5
	v_readlane_b32 s10, v246, 6
	v_readlane_b32 s11, v246, 7
	v_readlane_b32 s12, v246, 8
	v_readlane_b32 s13, v246, 9
	v_readlane_b32 s14, v246, 10
	v_readlane_b32 s15, v246, 11
	v_readlane_b32 s18, v246, 14
	v_readlane_b32 s19, v246, 15
	v_writelane_b32 v246, s0, 44
	s_cmpk_lt_i32 s2, 0x380
	s_mov_b32 s29, 0x2aaaaaab
	v_writelane_b32 v246, s1, 45
	s_cselect_b64 s[0:1], -1, 0
	s_abs_i32 s4, s30
	s_waitcnt lgkmcnt(0)
	v_cvt_f32_u32_e32 v0, s4
	s_sub_i32 s5, 0, s4
	s_add_i32 s3, s30, 0x1ff
	v_writelane_b32 v246, s0, 46
	v_rcp_iflag_f32_e32 v0, v0
	s_mov_b32 s46, 0x3ffff0
	v_writelane_b32 v246, s1, 47
	s_movk_i32 s0, 0x180
	v_mul_f32_e32 v0, 0x4f7ffffe, v0
	v_cvt_u32_f32_e32 v0, v0
	v_mov_b32_e32 v1, 0
	s_mov_b32 s36, 0x10000
	s_movk_i32 s38, 0xc000
	v_readfirstlane_b32 s6, v0
	s_mul_i32 s5, s5, s6
	s_mul_hi_u32 s5, s6, s5
	s_add_i32 s6, s6, s5
	s_mul_hi_u32 s5, s6, 0x180
	s_mul_i32 s5, s5, s4
	s_sub_i32 s5, 0x180, s5
	s_sub_i32 s7, s5, s4
	s_cmp_ge_u32 s5, s4
	s_cselect_b32 s5, s7, s5
	s_sub_i32 s7, s5, s4
	s_cmp_ge_u32 s5, s4
	s_cselect_b32 s5, s7, s5
	s_sub_i32 s1, 0x180, s5
	s_cmp_lt_i32 s2, s1
	s_cselect_b64 s[8:9], -1, 0
	s_lshl_b32 s68, s5, 1
	v_writelane_b32 v246, s8, 48
	s_cmp_lt_i32 s2, s68
	s_mov_b32 s41, 0xc2fc0000
	v_writelane_b32 v246, s9, 49
	s_cselect_b64 s[8:9], -1, 0
	s_sub_i32 s7, 0xfffffe01, s30
	s_xor_b32 s5, s3, s30
	s_max_i32 s3, s3, s7
	v_writelane_b32 v246, s8, 50
	s_mul_hi_u32 s7, s3, s6
	s_ashr_i32 s5, s5, 31
	v_writelane_b32 v246, s9, 51
	s_mul_i32 s8, s7, s4
	s_sub_i32 s3, s3, s8
	s_add_i32 s8, s7, 1
	s_sub_i32 s9, s3, s4
	s_cmp_ge_u32 s3, s4
	s_cselect_b32 s7, s8, s7
	s_cselect_b32 s3, s9, s3
	s_add_i32 s8, s7, 1
	s_cmp_ge_u32 s3, s4
	s_cselect_b32 s3, s8, s7
	s_xor_b32 s3, s3, s5
	s_sub_i32 s69, s3, s5
	s_mul_hi_u32 s3, s6, 0x580
	s_cmp_gt_i32 s69, 0
	s_mul_i32 s3, s3, s4
	s_cselect_b64 s[8:9], -1, 0
	s_sub_i32 s3, 0x580, s3
	s_sub_i32 s5, s3, s4
	s_cmp_ge_u32 s3, s4
	s_cselect_b32 s3, s5, s3
	s_sub_i32 s5, s3, s4
	s_cmp_ge_u32 s3, s4
	s_cselect_b32 s3, s5, s3
	s_sub_i32 s33, 0x580, s3
	v_writelane_b32 v246, s8, 52
	s_cmp_lt_i32 s2, s33
	s_cselect_b64 s[4:5], -1, 0
	v_writelane_b32 v246, s9, 53
	s_lshl_b32 s47, s3, 1
	v_writelane_b32 v246, s4, 54
	s_cmp_lt_i32 s2, s47
	s_mov_b32 s3, 0x18000
	v_writelane_b32 v246, s5, 55
	s_cselect_b64 s[4:5], -1, 0
	v_writelane_b32 v246, s4, 56
	s_add_i32 s39, s3, 0x400
	s_movk_i32 s3, 0x5000
	v_writelane_b32 v246, s5, 57
	s_addk_i32 s3, 0x400
	v_writelane_b32 v246, s3, 58
	s_mov_b32 s3, 0xd000
	s_addk_i32 s3, 0x400
	s_movk_i32 s37, 0x80
	v_mov_b32_e32 v163, 0x3000
	v_mov_b32_e32 v165, 1
	s_movk_i32 s49, 0xa0
	s_mov_b32 s42, 0x800000
	s_movk_i32 s43, 0x3fff
	s_movk_i32 s44, 0x300
	s_movk_i32 s45, 0xc00
	s_movk_i32 s48, 0x1a0
	v_writelane_b32 v246, s3, 59
	v_mov_b32_e32 v178, 0x3727c5ac
	s_movk_i32 s79, 0x1600
	v_mov_b32_e32 v179, 0x400
	v_mov_b32_e32 v180, 0x3e38aa3b
	v_mov_b32_e32 v181, 0x42800000
	v_not_b32_e32 v182, 63
	v_mov_b32_e32 v183, 0x1200
	v_mov_b32_e32 v184, 0xff800000
	v_mov_b32_e32 v164, 0x358637bd
	v_bfrev_b32_e32 v185, 0.5
	s_mov_b32 s3, 0
	s_mov_b32 s55, 0
	s_mov_b32 s70, 0x3fd744fd
	s_barrier
	s_branch .LBB0_278

.LBB0_379:
.LBB0_380:
	v_add_u32_e32 v172, v103, v124
	ds_read_b128 v[140:143], v172
	ds_read_b128 v[144:147], v172 offset:2560
	ds_read_b128 v[148:151], v172 offset:5120
	ds_read_b128 v[152:155], v172 offset:7680
	s_waitcnt lgkmcnt(3)
	v_mfma_f32_16x16x32_bf16 v[2:5], v[140:143], v[74:77], v[2:5]
	v_mfma_f32_16x16x32_bf16 v[6:9], v[140:143], v[78:81], v[6:9]
	s_waitcnt lgkmcnt(2)
	v_mfma_f32_16x16x32_bf16 v[10:13], v[144:147], v[74:77], v[10:13]
	v_mfma_f32_16x16x32_bf16 v[14:17], v[144:147], v[78:81], v[14:17]
	s_waitcnt lgkmcnt(1)
	v_mfma_f32_16x16x32_bf16 v[18:21], v[148:151], v[74:77], v[18:21]
	v_mfma_f32_16x16x32_bf16 v[22:25], v[148:151], v[78:81], v[22:25]
	s_waitcnt lgkmcnt(0)
	v_mfma_f32_16x16x32_bf16 v[26:29], v[152:155], v[74:77], v[26:29]
	v_mfma_f32_16x16x32_bf16 v[30:33], v[152:155], v[78:81], v[30:33]
	ds_bpermute_b32 v166, v126, v87
	ds_bpermute_b32 v167, v126, v136
	s_waitcnt lgkmcnt(0)
	v_add_f32_e32 v87, v87, v166
	v_add_f32_e32 v136, v136, v167
	ds_bpermute_b32 v166, v85, v87
	ds_bpermute_b32 v167, v85, v136
	s_waitcnt lgkmcnt(0)
	v_add_f32_e32 v87, v87, v166
	v_add_f32_e32 v136, v136, v167
	s_barrier
	v_div_scale_f32 v34, s[8:9], v87, v87, 1.0
	v_rcp_f32_e32 v35, v34
	s_nop 0
	v_fma_f32 v36, -v34, v35, 1.0
	v_fmac_f32_e32 v35, v36, v35
	v_div_scale_f32 v36, vcc, 1.0, v87, 1.0
	v_mul_f32_e32 v37, v36, v35
	v_fma_f32 v38, -v34, v37, v36
	v_fmac_f32_e32 v37, v38, v35
	v_fma_f32 v34, -v34, v37, v36
	v_div_fmas_f32 v34, v34, v35, v37
	v_div_fixup_f32 v34, v34, v87, 1.0
	v_div_scale_f32 v42, s[8:9], v136, v136, 1.0
	v_rcp_f32_e32 v43, v42
	s_nop 0
	v_fma_f32 v44, -v42, v43, 1.0
	v_fmac_f32_e32 v43, v44, v43
	v_div_scale_f32 v44, vcc, 1.0, v136, 1.0
	v_mul_f32_e32 v45, v44, v43
	v_fma_f32 v46, -v42, v45, v44
	v_fmac_f32_e32 v45, v46, v43
	v_fma_f32 v42, -v42, v45, v44
	v_div_fmas_f32 v42, v42, v43, v45
	v_div_fixup_f32 v42, v42, v136, 1.0
	s_lshl_b32 s4, s88, 7
	s_add_u32 s4, s76, s4
	s_addc_u32 s5, s77, 0
	v_and_b32_e32 v138, 15, v162
	v_add_u32_e32 v138, v93, v138
	v_ashrrev_i32_e32 v139, 31, v138
	v_lshlrev_b64 v[138:139], 11, v[138:139]
	v_lshl_add_u64 v[138:139], s[4:5], 0, v[138:139]
	v_bfe_u32 v166, v162, 4, 2
	v_lshlrev_b32_e32 v166, 3, v166
	v_mov_b32_e32 v167, 0
	v_lshl_add_u64 v[138:139], v[138:139], 0, v[166:167]
	v_add_co_u32_e32 v166, vcc, 0x8000, v138
	s_nop 1
	v_addc_co_u32_e32 v167, vcc, 0, v139, vcc
	v_mul_f32_e32 v2, v2, v34
	v_mul_f32_e32 v3, v3, v34
	v_mul_f32_e32 v4, v4, v34
	v_mul_f32_e32 v5, v5, v34
	v_cvt_pk_bf16_f32 v168, v2, v3
	v_cvt_pk_bf16_f32 v169, v4, v5
	global_store_dwordx2 v[138:139], v[168:169], off
	v_mul_f32_e32 v6, v6, v42
	v_mul_f32_e32 v7, v7, v42
	v_mul_f32_e32 v8, v8, v42
	v_mul_f32_e32 v9, v9, v42
	v_cvt_pk_bf16_f32 v170, v6, v7
	v_cvt_pk_bf16_f32 v171, v8, v9
	global_store_dwordx2 v[166:167], v[170:171], off
	v_mul_f32_e32 v10, v10, v34
	v_mul_f32_e32 v11, v11, v34
	v_mul_f32_e32 v12, v12, v34
	v_mul_f32_e32 v13, v13, v34
	v_cvt_pk_bf16_f32 v168, v10, v11
	v_cvt_pk_bf16_f32 v169, v12, v13
	global_store_dwordx2 v[138:139], v[168:169], off offset:32
	v_mul_f32_e32 v14, v14, v42
	v_mul_f32_e32 v15, v15, v42
	v_mul_f32_e32 v16, v16, v42
	v_mul_f32_e32 v17, v17, v42
	v_cvt_pk_bf16_f32 v170, v14, v15
	v_cvt_pk_bf16_f32 v171, v16, v17
	global_store_dwordx2 v[166:167], v[170:171], off offset:32
	v_mul_f32_e32 v18, v18, v34
	v_mul_f32_e32 v19, v19, v34
	v_mul_f32_e32 v20, v20, v34
	v_mul_f32_e32 v21, v21, v34
	v_cvt_pk_bf16_f32 v168, v18, v19
	v_cvt_pk_bf16_f32 v169, v20, v21
	global_store_dwordx2 v[138:139], v[168:169], off offset:64
	v_mul_f32_e32 v22, v22, v42
	v_mul_f32_e32 v23, v23, v42
	v_mul_f32_e32 v24, v24, v42
	v_mul_f32_e32 v25, v25, v42
	v_cvt_pk_bf16_f32 v170, v22, v23
	v_cvt_pk_bf16_f32 v171, v24, v25
	global_store_dwordx2 v[166:167], v[170:171], off offset:64
	v_mul_f32_e32 v26, v26, v34
	v_mul_f32_e32 v27, v27, v34
	v_mul_f32_e32 v28, v28, v34
	v_mul_f32_e32 v29, v29, v34
	v_cvt_pk_bf16_f32 v168, v26, v27
	v_cvt_pk_bf16_f32 v169, v28, v29
	global_store_dwordx2 v[138:139], v[168:169], off offset:96
	v_mul_f32_e32 v30, v30, v42
	v_mul_f32_e32 v31, v31, v42
	v_mul_f32_e32 v32, v32, v42
	v_mul_f32_e32 v33, v33, v42
	v_cvt_pk_bf16_f32 v170, v30, v31
	v_cvt_pk_bf16_f32 v171, v32, v33
	global_store_dwordx2 v[166:167], v[170:171], off offset:96
	s_add_i32 s87, s87, s30
	s_cmpk_gt_i32 s87, 0x3ff
	s_cbranch_scc1 .LBB0_401
.LBB0_381:
	s_ashr_i32 s4, s87, 4
	s_lshl_b32 s9, s4, 8
	s_and_b32 s88, s87, 15
	s_add_i32 s5, s9, 0xffffff80
	s_cmp_gt_i32 s4, 0
	s_cselect_b32 s8, s5, 0
	s_lshl_b32 s4, s88, 7
	s_add_u32 s58, s60, s4
	s_addc_u32 s59, s61, 0
	s_lshl_b32 s4, s87, 19
	s_and_b32 s10, s4, 0x600000
	s_add_u32 s4, s72, s10
	s_addc_u32 s5, s73, 0
	s_add_u32 s10, s74, s10
	v_readlane_b32 s12, v246, 0
	s_addc_u32 s11, s75, 0
	s_or_b32 s54, s88, s86
	v_readlane_b32 s16, v246, 4
	v_readlane_b32 s17, v246, 5
	v_readlane_b32 s20, v246, 8
	v_readlane_b32 s21, v246, 9
	s_lshl_b64 s[80:81], s[54:55], 2
	s_mov_b64 s[16:17], s[20:21]
	s_add_u32 s80, s16, s80
	s_addc_u32 s81, s17, s81
	v_mov_b32_e32 v6, v162
	global_load_dword v14, v1, s[80:81]
	s_sub_i32 s80, s9, s8
	v_ashrrev_i32_e32 v0, 1, v6
	v_and_b32_e32 v0, 0xffffffe0, v0
	v_and_b32_e32 v13, 31, v6
	v_add_u32_e32 v93, s9, v0
	v_or_b32_e32 v86, v93, v13
	v_ashrrev_i32_e32 v87, 31, v86
	v_lshlrev_b64 v[82:83], 11, v[86:87]
	s_mov_b32 s9, s55
	v_bfe_u32 v12, v6, 5, 1
	v_lshl_add_u64 v[2:3], s[58:59], 0, v[82:83]
	v_and_b32_e32 v120, 15, v6
	v_bfe_u32 v121, v6, 4, 2
	v_add_u32_e32 v122, v93, v120
	v_ashrrev_i32_e32 v123, 31, v122
	v_lshlrev_b64 v[116:117], 11, v[122:123]
	v_lshl_add_u64 v[116:117], s[58:59], 0, v[116:117]
	v_lshlrev_b32_e32 v120, 4, v121
	v_mov_b32_e32 v121, 0
	v_lshl_add_u64 v[116:117], v[116:117], 0, v[120:121]
	v_add_co_u32_e32 v118, vcc, 0x8000, v116
	s_nop 1
	v_addc_co_u32_e32 v119, vcc, 0, v117, vcc
	s_addk_i32 s80, 0x100
	s_lshl_b64 s[58:59], s[8:9], 7
	v_lshlrev_b32_e32 v0, 4, v12
	s_add_u32 s58, s4, s58
	v_ashrrev_i32_e32 v7, 31, v6
	v_lshl_add_u64 v[16:17], v[2:3], 0, v[0:1]
	s_addc_u32 s59, s5, s59
	v_lshlrev_b64 v[2:3], 4, v[6:7]
	v_lshl_add_u64 v[4:5], s[58:59], 0, v[2:3]
	global_load_dwordx4 v[50:53], v[116:117], off
	global_load_dwordx4 v[54:57], v[116:117], off offset:64
	global_load_dwordx4 v[58:61], v[118:119], off
	global_load_dwordx4 v[62:65], v[4:5], off
	v_lshrrev_b32_e32 v4, 29, v7
	v_add_u32_e32 v7, v6, v4
	s_lshl_b64 s[58:59], s[8:9], 1
	v_ashrrev_i32_e32 v18, 3, v7
	v_and_b32_e32 v7, -8, v7
	s_add_u32 s58, s10, s58
	v_ashrrev_i32_e32 v19, 31, v18
	v_sub_u32_e32 v7, v6, v7
	s_addc_u32 s59, s11, s59
	v_lshlrev_b64 v[4:5], 15, v[18:19]
	v_lshlrev_b32_e32 v8, 3, v7
	v_lshl_add_u64 v[10:11], s[58:59], 0, v[4:5]
	v_ashrrev_i32_e32 v9, 31, v8
	v_lshl_add_u64 v[10:11], v[8:9], 1, v[10:11]
	global_load_dwordx4 v[66:69], v[118:119], off offset:64
	global_load_dwordx4 v[70:73], v[10:11], off
	v_readlane_b32 s13, v246, 1
	v_readlane_b32 s14, v246, 2
	v_readlane_b32 s15, v246, 3
	v_readlane_b32 s18, v246, 6
	v_readlane_b32 s19, v246, 7
	v_readlane_b32 s22, v246, 10
	v_readlane_b32 s23, v246, 11
	v_readlane_b32 s24, v246, 12
	v_readlane_b32 s25, v246, 13
	v_readlane_b32 s26, v246, 14
	v_readlane_b32 s27, v246, 15
	v_mul_lo_u32 v15, v18, s49
	v_lshlrev_b32_e32 v7, 4, v7
	v_add3_u32 v94, s78, v15, v7
	s_cmpk_lt_i32 s80, 0x80
	s_waitcnt vmcnt(2)
	ds_write_b128 v94, v[62:65]
	s_waitcnt vmcnt(0)
	ds_write_b128 v94, v[70:73] offset:20480
	s_cbranch_scc1 .LBB0_383
	s_or_b32 s54, s8, 64
	s_lshl_b64 s[58:59], s[54:55], 7
	s_add_u32 s58, s4, s58
	s_addc_u32 s59, s5, s59
	v_lshl_add_u64 v[16:17], s[58:59], 0, v[2:3]
	global_load_dwordx4 v[62:65], v[16:17], off
	global_load_dwordx4 v[70:73], v[10:11], off offset:128

.LBB0_385:
	v_cndmask_b32_e64 v87, 0, 1.0, vcc
	s_andn2_b64 vcc, exec, s[58:59]
	s_mov_b32 s58, 0
	s_cbranch_vccnz .LBB0_400
	v_lshl_add_u64 v[88:89], s[4:5], 0, v[2:3]
	v_lshl_add_u64 v[2:3], s[10:11], 0, v[4:5]
	s_ashr_i32 s9, s80, 6
	v_lshl_add_u64 v[90:91], v[8:9], 1, v[2:3]
	v_mul_u32_u24_e32 v92, 0x90, v13
	v_lshlrev_b32_e32 v2, 2, v6
	v_readlane_b32 s4, v246, 58
	s_add_i32 s89, s9, -2
	v_mul_f32_e32 v100, 0x3fb8aa3b, v14
	v_add_u32_e32 v95, 63, v93
	v_add3_u32 v96, s78, v92, v0
	v_or_b32_e32 v97, 31, v93
	v_lshlrev_b32_e32 v84, 2, v12
	v_xor_b32_e32 v85, 0x80, v2
	v_mov_b32_e32 v2, v1
	v_mov_b32_e32 v3, v1
	v_mov_b32_e32 v4, v1
	v_mov_b32_e32 v5, v1
	v_mov_b32_e32 v6, v1
	v_mov_b32_e32 v7, v1
	v_mov_b32_e32 v8, v1
	v_mov_b32_e32 v9, v1
	v_mov_b32_e32 v10, v1
	v_mov_b32_e32 v11, v1
	v_mov_b32_e32 v12, v1
	v_mov_b32_e32 v13, v1
	v_mov_b32_e32 v14, v1
	v_mov_b32_e32 v15, v1
	v_mov_b32_e32 v16, v1
	v_mov_b32_e32 v17, v1
	v_mov_b32_e32 v18, v1
	v_mov_b32_e32 v19, v1
	v_mov_b32_e32 v20, v1
	v_mov_b32_e32 v21, v1
	v_mov_b32_e32 v22, v1
	v_mov_b32_e32 v23, v1
	v_mov_b32_e32 v24, v1
	v_mov_b32_e32 v25, v1
	v_mov_b32_e32 v26, v1
	v_mov_b32_e32 v27, v1
	v_mov_b32_e32 v28, v1
	v_mov_b32_e32 v29, v1
	v_mov_b32_e32 v30, v1
	v_mov_b32_e32 v31, v1
	v_mov_b32_e32 v32, v1
	v_mov_b32_e32 v33, v1
	v_mov_b32_e32 v103, s4
	v_mov_b32_e32 v78, 0
	v_mov_b32_e32 v79, 0
	v_mov_b32_e32 v80, 0
	v_mov_b32_e32 v81, 0
	v_mov_b32_e32 v74, 0
	v_mov_b32_e32 v75, 0
	v_mov_b32_e32 v76, 0
	v_mov_b32_e32 v77, 0
	v_and_b32_e32 v138, 15, v162
	v_bfe_u32 v139, v162, 4, 2
	v_lshrrev_b32_e32 v166, 3, v138
	v_lshl_add_u32 v166, v166, 3, v138
	v_mul_u32_u24_e32 v166, 0xa0, v166
	v_lshlrev_b32_e32 v167, 4, v139
	v_add3_u32 v96, s78, v166, v167
	v_mul_u32_u24_e32 v166, 0xa0, v138
	v_add_u32_e32 v124, v166, v167
	v_lshrrev_b32_e32 v166, 1, v139
	v_lshlrev_b32_e32 v166, 3, v166
	v_lshl_add_u32 v166, v139, 2, v166
	v_sub_u32_e32 v125, v166, v138
	v_and_b32_e32 v166, 63, v162
	v_xor_b32_e32 v167, 16, v166
	v_lshlrev_b32_e32 v126, 2, v167
	v_cmp_gt_u32_e32 vcc, 16, v166
	v_mov_b32_e32 v127, v100
	s_nop 1
	v_cndmask_b32_e64 v87, 0, 1.0, vcc
	v_cndmask_b32_e64 v136, 0, 1.0, vcc
	v_readfirstlane_b32 s98, v93
	v_sub_f32_e32 v128, 0, v100
	v_sub_f32_e32 v129, 0, v100
	v_sub_f32_e32 v130, 0, v100
	v_sub_f32_e32 v131, 0, v100
	v_sub_f32_e32 v132, 0, v100
	v_sub_f32_e32 v133, 0, v100
	v_sub_f32_e32 v134, 0, v100
	v_sub_f32_e32 v135, 0, v100
	s_and_b32 s4, s58, 1
	s_add_i32 s90, s58, 1
	s_cmp_ge_i32 s90, s9
	s_cbranch_scc1 .LBB0_388
.LBB0_387:
	s_mul_hi_u32 s10, s90, 0xaaaaaaab
	s_lshr_b32 s10, s10, 1
	s_xor_b32 s5, s4, 1
	s_mul_i32 s10, s10, 3
	s_mulk_i32 s5, 0x2800
	s_sub_i32 s10, s90, s10
	s_mulk_i32 s10, 0x2800
	v_add_u32_e32 v34, s5, v94
	s_waitcnt vmcnt(1)
	ds_write_b128 v34, v[62:65]
	v_add_u32_e32 v34, s10, v94
	s_waitcnt vmcnt(0)
	ds_write_b128 v34, v[70:73] offset:20480

.LBB0_390:
	s_mul_hi_u32 s5, s58, 0xaaaaaaab
	s_lshr_b32 s5, s5, 1
	s_mul_i32 s5, s5, 3
	s_sub_i32 s5, s58, s5
	s_mulk_i32 s4, 0x2800
	s_mulk_i32 s5, 0x2800
	s_add_i32 s11, s5, 0x400
	v_add_u32_e32 v98, s4, v96
.Lw3_h0:
	s_mov_b32 s101, s10
	s_sub_i32 s99, s98, s101
	s_add_i32 s100, s99, 63
	s_cmp_lt_u32 s100, 222
	s_cbranch_scc0 .Lw3_h0_end
	v_mov_b32_e32 v173, v98
	v_add_u32_e32 v172, v103, v124
	s_add_i32 s4, s11, 0x5000
	ds_read_b128 v[140:143], v173
	ds_read_b128 v[144:147], v173 offset:1280
	ds_read_b128 v[148:151], v173 offset:64
	ds_read_b128 v[152:155], v173 offset:1344
	v_mov_b32_e32 v103, s4
	s_waitcnt lgkmcnt(3)
	v_mfma_f32_16x16x32_bf16 v[34:37], v[140:143], v[50:53], v[128:131]
	v_mfma_f32_16x16x32_bf16 v[38:41], v[140:143], v[58:61], v[132:135]
	ds_read_b128 v[156:159], v172
	s_waitcnt lgkmcnt(3)
	v_mfma_f32_16x16x32_bf16 v[42:45], v[144:147], v[50:53], v[128:131]
	v_mfma_f32_16x16x32_bf16 v[46:49], v[144:147], v[58:61], v[132:135]
	ds_read_b128 v[140:143], v172 offset:2560
	s_waitcnt lgkmcnt(3)
	v_mfma_f32_16x16x32_bf16 v[34:37], v[148:151], v[54:57], v[34:37]
	v_mfma_f32_16x16x32_bf16 v[38:41], v[148:151], v[66:69], v[38:41]
	ds_read_b128 v[144:147], v172 offset:5120
	s_waitcnt lgkmcnt(3)
	v_mfma_f32_16x16x32_bf16 v[42:45], v[152:155], v[54:57], v[42:45]
	v_mfma_f32_16x16x32_bf16 v[46:49], v[152:155], v[66:69], v[46:49]
	ds_read_b128 v[148:151], v172 offset:7680
	s_waitcnt lgkmcnt(3)
	v_mfma_f32_16x16x32_bf16 v[2:5], v[156:159], v[74:77], v[2:5]
	v_mfma_f32_16x16x32_bf16 v[6:9], v[156:159], v[78:81], v[6:9]
	s_waitcnt lgkmcnt(2)
	v_mfma_f32_16x16x32_bf16 v[10:13], v[140:143], v[74:77], v[10:13]
	v_mfma_f32_16x16x32_bf16 v[14:17], v[140:143], v[78:81], v[14:17]
	s_waitcnt lgkmcnt(1)
	v_mfma_f32_16x16x32_bf16 v[18:21], v[144:147], v[74:77], v[18:21]
	v_mfma_f32_16x16x32_bf16 v[22:25], v[144:147], v[78:81], v[22:25]
	s_waitcnt lgkmcnt(0)
	v_mfma_f32_16x16x32_bf16 v[26:29], v[148:151], v[74:77], v[26:29]
	v_mfma_f32_16x16x32_bf16 v[30:33], v[148:151], v[78:81], v[30:33]
	s_cmp_lt_i32 s99, 31
	s_cbranch_scc1 .Lw3_h0_mask
	s_cmp_ge_i32 s99, 97
	s_cbranch_scc1 .Lw3_h0_wmask

.Lw3_h0_end:
.Lw3_h1:
	s_add_i32 s101, s10, 32
	s_sub_i32 s99, s98, s101
	s_add_i32 s100, s99, 63
	s_cmp_lt_u32 s100, 222
	s_cbranch_scc0 .Lw3_h1_end
	v_add_u32_e32 v173, 0x1400, v98
	v_add_u32_e32 v172, v103, v124
	s_add_i32 s4, s11, 0x5040
	ds_read_b128 v[140:143], v173
	ds_read_b128 v[144:147], v173 offset:1280
	ds_read_b128 v[148:151], v173 offset:64
	ds_read_b128 v[152:155], v173 offset:1344
	v_mov_b32_e32 v103, s4
	s_waitcnt lgkmcnt(3)
	v_mfma_f32_16x16x32_bf16 v[34:37], v[140:143], v[50:53], v[128:131]
	v_mfma_f32_16x16x32_bf16 v[38:41], v[140:143], v[58:61], v[132:135]
	ds_read_b128 v[156:159], v172
	s_waitcnt lgkmcnt(3)
	v_mfma_f32_16x16x32_bf16 v[42:45], v[144:147], v[50:53], v[128:131]
	v_mfma_f32_16x16x32_bf16 v[46:49], v[144:147], v[58:61], v[132:135]
	ds_read_b128 v[140:143], v172 offset:2560
	s_waitcnt lgkmcnt(3)
	v_mfma_f32_16x16x32_bf16 v[34:37], v[148:151], v[54:57], v[34:37]
	v_mfma_f32_16x16x32_bf16 v[38:41], v[148:151], v[66:69], v[38:41]
	ds_read_b128 v[144:147], v172 offset:5120
	s_waitcnt lgkmcnt(3)
	v_mfma_f32_16x16x32_bf16 v[42:45], v[152:155], v[54:57], v[42:45]
	v_mfma_f32_16x16x32_bf16 v[46:49], v[152:155], v[66:69], v[46:49]
	ds_read_b128 v[148:151], v172 offset:7680
	s_waitcnt lgkmcnt(3)
	v_mfma_f32_16x16x32_bf16 v[2:5], v[156:159], v[74:77], v[2:5]
	v_mfma_f32_16x16x32_bf16 v[6:9], v[156:159], v[78:81], v[6:9]
	s_waitcnt lgkmcnt(2)
	v_mfma_f32_16x16x32_bf16 v[10:13], v[140:143], v[74:77], v[10:13]
	v_mfma_f32_16x16x32_bf16 v[14:17], v[140:143], v[78:81], v[14:17]
	s_waitcnt lgkmcnt(1)
	v_mfma_f32_16x16x32_bf16 v[18:21], v[144:147], v[74:77], v[18:21]
	v_mfma_f32_16x16x32_bf16 v[22:25], v[144:147], v[78:81], v[22:25]
	s_waitcnt lgkmcnt(0)
	v_mfma_f32_16x16x32_bf16 v[26:29], v[148:151], v[74:77], v[26:29]
	v_mfma_f32_16x16x32_bf16 v[30:33], v[148:151], v[78:81], v[30:33]
	s_cmp_lt_i32 s99, 31
	s_cbranch_scc1 .Lw3_h1_mask
	s_cmp_ge_i32 s99, 97
	s_cbranch_scc1 .Lw3_h1_wmask

.LBB0_763:
	s_and_b32 s4, s77, 1
	s_add_i32 s5, s77, s4
	s_sub_i32 s4, 0, s4
	s_xor_b32 s4, s2, s4
	s_mul_i32 s5, s5, s30
	s_add_i32 s4, s5, s4
	s_cmpk_gt_i32 s4, 0x1ff
	s_cbranch_scc1 .LBB0_762
	s_and_b32 s86, s4, 7
	s_mul_i32 s5, s86, 0x180
	s_add_u32 s10, s40, s5
	s_addc_u32 s11, s60, 0
	s_mul_i32 s5, s86, 0x600000
	s_add_u32 s6, s61, s5
	s_addc_u32 s7, s72, 0
	s_lshl_b32 s5, s86, 22
	s_add_u32 s8, s73, s5
	v_mov_b32_e32 v22, v162
	s_addc_u32 s9, s74, 0
	s_lshl_b32 s4, s4, 5
	s_and_b32 s54, s4, 0xffffff00
	v_ashrrev_i32_e32 v0, 1, v22
	v_and_b32_e32 v0, 0xffffffe0, v0
	v_subrev_u32_e32 v38, s54, v0
	v_and_b32_e32 v36, 31, v22
	v_add_u32_e32 v186, 0x3f00, v38
	v_bfe_u32 v37, v22, 5, 1
	v_or_b32_e32 v158, v186, v36
	v_and_b32_e32 v4, 15, v22
	v_bfe_u32 v5, v22, 4, 2
	v_add_u32_e32 v158, v186, v4
	v_lshlrev_b32_e32 v0, 4, v5
	v_mov_b64_e32 v[2:3], s[10:11]
	v_mad_i64_i32 v[2:3], s[4:5], v158, s45, v[2:3]
	v_lshl_add_u64 v[2:3], v[2:3], 0, v[0:1]
	v_add_co_u32_e32 v4, vcc, 0xc000, v2
	s_nop 1
	v_addc_co_u32_e32 v5, vcc, 0, v3, vcc
	global_load_dwordx4 v[82:85], v[2:3], off
	global_load_dwordx4 v[86:89], v[2:3], off offset:64
	global_load_dwordx4 v[90:93], v[2:3], off offset:128
	global_load_dwordx4 v[94:97], v[2:3], off offset:192
	global_load_dwordx4 v[98:101], v[2:3], off offset:256
	global_load_dwordx4 v[102:105], v[2:3], off offset:320
	global_load_dwordx4 v[106:109], v[4:5], off
	global_load_dwordx4 v[110:113], v[4:5], off offset:64
	global_load_dwordx4 v[114:117], v[4:5], off offset:128
	global_load_dwordx4 v[118:121], v[4:5], off offset:192
	global_load_dwordx4 v[122:125], v[4:5], off offset:256
	global_load_dwordx4 v[126:129], v[4:5], off offset:320
	v_add_u32_e32 v24, 0x200, v22
	v_ashrrev_i32_e32 v25, 31, v24
	v_ashrrev_i32_e32 v23, 31, v22
	v_lshrrev_b32_e32 v18, 29, v25
	v_lshrrev_b32_e32 v12, 29, v23
	v_add_u32_e32 v20, v24, v18
	v_add_u32_e32 v14, v22, v12
	v_ashrrev_i32_e32 v32, 3, v20
	v_and_b32_e32 v20, -8, v20
	v_lshlrev_b64 v[166:167], 4, v[24:25]
	v_add_u32_e32 v26, 0x400, v22
	v_ashrrev_i32_e32 v28, 3, v14
	v_and_b32_e32 v14, -8, v14
	v_ashrrev_i32_e32 v33, 31, v32
	v_sub_u32_e32 v25, v24, v20
	v_lshlrev_b64 v[160:161], 4, v[22:23]
	v_ashrrev_i32_e32 v27, 31, v26
	v_ashrrev_i32_e32 v29, 31, v28
	v_sub_u32_e32 v23, v22, v14
	v_lshlrev_b64 v[174:175], 15, v[32:33]
	v_lshlrev_b32_e32 v176, 3, v25
	v_lshlrev_b64 v[168:169], 4, v[26:27]
	v_lshlrev_b64 v[170:171], 15, v[28:29]
	v_lshlrev_b32_e32 v172, 3, v23
	v_lshl_add_u64 v[18:19], s[8:9], 0, v[174:175]
	v_ashrrev_i32_e32 v177, 31, v176
	v_lshl_add_u64 v[2:3], s[6:7], 0, v[160:161]
	v_lshl_add_u64 v[6:7], s[6:7], 0, v[166:167]
	v_lshl_add_u64 v[10:11], s[6:7], 0, v[168:169]
	v_lshl_add_u64 v[12:13], s[8:9], 0, v[170:171]
	v_ashrrev_i32_e32 v173, 31, v172
	v_lshl_add_u64 v[34:35], v[176:177], 1, v[18:19]
	global_load_dwordx4 v[2:5], v[2:3], off
	s_nop 0
	global_load_dwordx4 v[6:9], v[6:7], off
	v_lshl_add_u64 v[30:31], v[172:173], 1, v[12:13]
	global_load_dwordx4 v[10:13], v[10:11], off
	s_nop 0
	global_load_dwordx4 v[14:17], v[30:31], off
	global_load_dwordx4 v[18:21], v[34:35], off
	s_sub_i32 s4, 0x4000, s54
	v_and_b32_e32 v27, 63, v22
	v_ashrrev_i32_e32 v159, 31, v158
	v_mul_hi_i32 v29, v22, s29
	v_lshrrev_b32_e32 v33, 31, v29
	v_ashrrev_i32_e32 v29, 2, v29
	v_add_u32_e32 v29, v29, v33
	v_mul_lo_u32 v187, v29, s48
	v_mul_lo_u32 v29, v29, 24
	v_sub_u32_e32 v22, v22, v29
	v_lshlrev_b32_e32 v188, 4, v22
	v_add3_u32 v22, s78, v187, v188
	s_waitcnt vmcnt(4)
	ds_write_b128 v22, v[2:5]
	v_mul_hi_i32 v2, v24, s29
	v_lshrrev_b32_e32 v3, 31, v2
	v_ashrrev_i32_e32 v2, 2, v2
	v_add_u32_e32 v2, v2, v3
	v_mul_lo_u32 v189, v2, s48
	v_mul_lo_u32 v2, v2, 24
	v_sub_u32_e32 v2, v24, v2
	v_lshlrev_b32_e32 v190, 4, v2
	v_add3_u32 v2, s78, v189, v190
	s_waitcnt vmcnt(3)
	ds_write_b128 v2, v[6:9]
	v_mul_hi_i32 v2, v26, s29
	v_lshrrev_b32_e32 v3, 31, v2
	v_ashrrev_i32_e32 v2, 2, v2
	v_add_u32_e32 v2, v2, v3
	v_mul_lo_u32 v191, v2, s48
	v_mul_lo_u32 v2, v2, 24
	v_sub_u32_e32 v2, v26, v2
	v_lshlrev_b32_e32 v192, 4, v2
	s_movk_i32 s5, 0xa0
	v_add3_u32 v2, s78, v191, v192
	v_mul_lo_u32 v193, v28, s5
	v_lshlrev_b32_e32 v194, 4, v23
	s_waitcnt vmcnt(2)
	ds_write_b128 v2, v[10:13]
	v_add3_u32 v2, s78, v193, v194
	v_mul_lo_u32 v195, v32, s5
	v_lshlrev_b32_e32 v196, 4, v25
	s_add_u32 s10, s6, 0x6000
	s_waitcnt vmcnt(1)
	ds_write_b128 v2, v[14:17] offset:53248
	v_add3_u32 v2, s78, v195, v196
	s_addc_u32 s11, s7, 0
	s_waitcnt vmcnt(0)
	ds_write_b128 v2, v[18:21] offset:53248
	s_movk_i32 s49, 0xa0
	s_lshr_b32 s87, s4, 6
	v_mul_u32_u24_e32 v2, 0x190, v36
	v_add3_u32 v202, s78, v2, v0
	v_lshlrev_b32_e32 v2, 2, v27
	v_mov_b32_e32 v50, v1
	v_mov_b32_e32 v51, v1
	v_add_u32_e32 v201, 0x3f3f, v38
	v_add_u32_e32 v203, 0x3f1f, v38
	v_lshlrev_b32_e32 v197, 2, v37
	v_xor_b32_e32 v198, 0x80, v2
	v_mul_u32_u24_e32 v200, 0x90, v36
	v_mov_b32_e32 v52, v1
	v_mov_b32_e32 v53, v1
	v_mov_b32_e32 v54, v1
	v_mov_b32_e32 v55, v1
	v_mov_b32_e32 v56, v1
	v_mov_b32_e32 v57, v1
	v_mov_b32_e32 v58, v1
	v_mov_b32_e32 v59, v1
	v_mov_b32_e32 v60, v1
	v_mov_b32_e32 v61, v1
	v_mov_b32_e32 v62, v1
	v_mov_b32_e32 v63, v1
	v_mov_b32_e32 v64, v1
	v_mov_b32_e32 v65, v1
	v_readlane_b32 s5, v246, 59
	v_mov_b64_e32 v[34:35], v[50:51]
	v_mov_b64_e32 v[18:19], v[50:51]
	v_mov_b64_e32 v[2:3], v[50:51]
	s_mov_b32 s4, 0
	v_mov_b32_e32 v199, 0
	v_mov_b32_e32 v206, 0xf149f2ca
	v_mov_b32_e32 v209, s5
	v_mov_b32_e32 v154, 0
	v_mov_b32_e32 v155, 0
	v_mov_b32_e32 v156, 0
	v_mov_b32_e32 v157, 0
	v_mov_b32_e32 v150, 0
	v_mov_b32_e32 v151, 0
	v_mov_b32_e32 v152, 0
	v_mov_b32_e32 v153, 0
	v_mov_b64_e32 v[36:37], v[52:53]
	v_mov_b64_e32 v[38:39], v[54:55]
	v_mov_b64_e32 v[40:41], v[56:57]
	v_mov_b64_e32 v[42:43], v[58:59]
	v_mov_b64_e32 v[44:45], v[60:61]
	v_mov_b64_e32 v[46:47], v[62:63]
	v_mov_b64_e32 v[48:49], v[64:65]
	v_mov_b64_e32 v[20:21], v[52:53]
	v_mov_b64_e32 v[22:23], v[54:55]
	v_mov_b64_e32 v[24:25], v[56:57]
	v_mov_b64_e32 v[26:27], v[58:59]
	v_mov_b64_e32 v[28:29], v[60:61]
	v_mov_b64_e32 v[30:31], v[62:63]
	v_mov_b64_e32 v[32:33], v[64:65]
	v_mov_b64_e32 v[4:5], v[52:53]
	v_mov_b64_e32 v[6:7], v[54:55]
	v_mov_b64_e32 v[8:9], v[56:57]
	v_mov_b64_e32 v[10:11], v[58:59]
	v_mov_b64_e32 v[12:13], v[60:61]
	v_mov_b64_e32 v[14:15], v[62:63]
	v_mov_b64_e32 v[16:17], v[64:65]
	v_and_b32_e32 v239, 15, v162
	v_bfe_u32 v244, v162, 4, 2
	v_lshrrev_b32_e32 v245, 3, v239
	v_lshl_add_u32 v245, v245, 3, v239
	v_mul_u32_u24_e32 v245, 0x1a0, v245
	v_lshlrev_b32_e32 v205, 4, v244
	v_add3_u32 v202, s78, v245, v205
	v_mul_u32_u24_e32 v245, 0xa0, v239
	v_add_u32_e32 v200, v245, v205
	v_lshrrev_b32_e32 v245, 1, v244
	v_lshlrev_b32_e32 v245, 3, v245
	v_lshl_add_u32 v245, v244, 2, v245
	v_sub_u32_e32 v197, v245, v239
	v_and_b32_e32 v245, 63, v162
	v_xor_b32_e32 v245, 16, v245
	v_lshlrev_b32_e32 v208, 2, v245
	v_mov_b32_e32 v206, 0
	v_mov_b32_e32 v201, 0
	v_mov_b32_e32 v203, 0
	s_mov_b32 s21, 0
	v_mov_b32_e32 v210, 0
	v_mov_b32_e32 v211, 0
	v_mov_b32_e32 v212, 0
	v_mov_b32_e32 v213, 0
	v_mov_b32_e32 v214, 0
	v_mov_b32_e32 v215, 0
	v_mov_b32_e32 v216, 0
	v_mov_b32_e32 v217, 0
	v_readfirstlane_b32 s12, v186
	v_add_u32_e32 v244, 0, v162
	v_mul_u32_u24_e32 v245, 0x9d9, v244
	v_lshrrev_b32_e32 v245, 16, v245
	v_mul_u32_u24_e32 v239, 26, v245
	v_sub_u32_e32 v244, v244, v239
	v_min_u32_e32 v244, 23, v244
	v_mul_u32_u24_e32 v245, 0x180, v245
	v_lshl_add_u32 v130, v244, 4, v245
	v_add_u32_e32 v244, 512, v162
	v_mul_u32_u24_e32 v245, 0x9d9, v244
	v_lshrrev_b32_e32 v245, 16, v245
	v_mul_u32_u24_e32 v239, 26, v245
	v_sub_u32_e32 v244, v244, v239
	v_min_u32_e32 v244, 23, v244
	v_mul_u32_u24_e32 v245, 0x180, v245
	v_lshl_add_u32 v131, v244, 4, v245
	v_add_u32_e32 v244, 1024, v162
	v_mul_u32_u24_e32 v245, 0x9d9, v244
	v_lshrrev_b32_e32 v245, 16, v245
	v_mul_u32_u24_e32 v239, 26, v245
	v_sub_u32_e32 v244, v244, v239
	v_min_u32_e32 v244, 23, v244
	v_mul_u32_u24_e32 v245, 0x180, v245
	v_lshl_add_u32 v132, v244, 4, v245
	v_add_u32_e32 v244, 1536, v162
	v_mul_u32_u24_e32 v245, 0x9d9, v244
	v_lshrrev_b32_e32 v245, 16, v245
	v_mul_u32_u24_e32 v239, 26, v245
	v_sub_u32_e32 v244, v244, v239
	v_min_u32_e32 v244, 23, v244
	v_mul_u32_u24_e32 v245, 0x180, v245
	v_lshl_add_u32 v133, v244, 4, v245
	v_add_u32_e32 v244, 0, v162
	v_mul_u32_u24_e32 v245, 0x667, v244
	v_lshrrev_b32_e32 v245, 14, v245
	v_mul_u32_u24_e32 v239, 10, v245
	v_sub_u32_e32 v244, v244, v239
	v_min_u32_e32 v244, 7, v244
	v_lshlrev_b32_e32 v245, 15, v245
	v_lshl_add_u32 v134, v244, 4, v245
	v_add_u32_e32 v244, 512, v162
	v_mul_u32_u24_e32 v245, 0x667, v244
	v_lshrrev_b32_e32 v245, 14, v245
	v_mul_u32_u24_e32 v239, 10, v245
	v_sub_u32_e32 v244, v244, v239
	v_min_u32_e32 v244, 7, v244
	v_lshlrev_b32_e32 v245, 15, v245
	v_lshl_add_u32 v135, v244, 4, v245
	v_add_u32_e32 v244, 1024, v162
	v_mul_u32_u24_e32 v245, 0x667, v244
	v_lshrrev_b32_e32 v245, 14, v245
	v_mul_u32_u24_e32 v239, 10, v245
	v_sub_u32_e32 v244, v244, v239
	v_min_u32_e32 v244, 7, v244
	v_lshlrev_b32_e32 v245, 15, v245
	v_lshl_add_u32 v136, v244, 4, v245
	s_nop 3
	s_lshr_b32 s22, s12, 5
	s_and_b32 s22, s22, 7
	s_lshl_b32 s23, s22, 10
	s_waitcnt lgkmcnt(0)
	s_barrier
	s_and_b32 s5, s4, 1
	s_add_i32 s88, s4, 1
	s_cmp_ge_u32 s88, s87
	s_cbranch_scc1 .LBB0_766
